# P3 K-loop first iteration peeled with C = 0 (67 zeroing moves per unit removed)
# speedup vs baseline: 1.0004x; 1.0004x over previous
; #define PG8_STAGE(bufoff, gbase, voff) do { _Pragma("unroll") for (int _i = 0; _i < 2; ++_i) \
;         __builtin_amdgcn_global_load_lds((const unsigned*)((const char*)(gbase) + (voff)[_i]), (PG8_LAS unsigned*)(lds + (bufoff) + ldsw + _i * 8192), 16, 0, 0); } while (0)
; #define PG8_LDA(dst, b, h) do { _Pragma("unroll") for (int m = 0; m < 4; ++m) _Pragma("unroll") for (int k = 0; k < 2; ++k) dst[m][k] = *(const PG8_LAS bf16x8*)(lds + PG8_SA(b, h) + aoff + m * 2048 + k * 1024); } while (0)
; #define PG8_LDB(dst, b, h) do { _Pragma("unroll") for (int n = 0; n < 2; ++n) _Pragma("unroll") for (int k = 0; k < 2; ++k) dst[n][k] = *(const PG8_LAS bf16x8*)(lds + PG8_SB(b, h) + boff + n * 2048 + k * 1024); } while (0)
; #define PG8_MMA(ai, bj, At, Bt) do { __builtin_amdgcn_s_setprio(1); _Pragma("unroll") for (int m = 0; m < 4; ++m) _Pragma("unroll") for (int n = 0; n < 2; ++n) _Pragma("unroll") for (int k = 0; k < 2; ++k) \
;         acc[ai][bj][m][n] = __builtin_amdgcn_mfma_f32_16x16x32_bf16(Bt[n][k], At[m][k], acc[ai][bj][m][n], 0, 0, 0); __builtin_amdgcn_s_setprio(0); } while (0)
; #define PG8_WAIT_V(n) asm volatile("s_waitcnt vmcnt(" #n ")" ::: "memory")
; #define PG8_WAIT_L(n) asm volatile("s_waitcnt lgkmcnt(" #n ")" ::: "memory")
; #define PG8_BAR __builtin_amdgcn_s_barrier()
; #define PG8_SCHED __builtin_amdgcn_sched_barrier(0)
; template <class Epi, class Sched, bool ALIGN_EPI = false, bool SP2 = false>
; __device__ __forceinline__ void gemm_phase(PG8_LAS unsigned char* lds, const Gemm g, const Sched& S, const Epi& E) {
;     ...
;             PG8_LDB(B0, 0, 0); PG8_LDB(B1, 0, 1); PG8_SCHED; PG8_LDA(At, 0, 0); PG8_STAGE(PG8_SA(1, 1), a1 + hstep, voffA);
;             PG8_WAIT_V(8); PG8_WAIT_L(0); PG8_BAR; PG8_MMA(0, 0, At, B0); PG8_MMA(0, 1, At, B1); PG8_BAR; PG8_SCHED;
;             PG8_LDA(At, 0, 1); PG8_STAGE(PG8_SB(0, 0), b2, voffB); PG8_STAGE(PG8_SB(0, 1), b2 + hstepB, voffB); PG8_STAGE(PG8_SA(0, 0), a2, voffA);
;             PG8_WAIT_V(8); PG8_WAIT_L(0); PG8_BAR; PG8_MMA(1, 0, At, B0); PG8_MMA(1, 1, At, B1); PG8_BAR; PG8_SCHED;
.LBB0_379:
	s_ashr_i32 s21, s20, 31
	s_lshl_b64 s[0:1], s[20:21], 19
	s_add_u32 s22, s40, s0
	s_addc_u32 s23, s41, s1
	s_and_b64 s[0:1], s[4:5], exec
	s_cselect_b32 s0, s23, s29
	s_cselect_b32 s1, s22, s28
	s_ashr_i32 s19, s18, 31
	s_lshl_b64 s[24:25], s[18:19], 19
	s_add_u32 s24, s68, s24
	s_addc_u32 s25, s69, s25
	s_and_b64 s[44:45], s[4:5], exec
	s_cselect_b32 s19, s25, s47
	s_cselect_b32 s21, s24, s46
	s_lshl_b32 s27, s27, 2
	s_or_b32 s44, s27, s80
	s_add_u32 s27, s46, 0x10000
	v_lshl_add_u64 v[182:183], s[28:29], 0, v[210:211]
	v_lshl_add_u64 v[184:185], s[28:29], 0, v[212:213]
	s_addc_u32 s45, s47, 0
	s_mov_b32 s56, -2
	s_mov_b64 s[46:47], 0
	s_add_u32 s48, s28, s46
	v_add_u32_e32 v3, s87, v221
	s_addc_u32 s49, s29, s47
	ds_read_b128 v[134:137], v3
	ds_read_b128 v[138:141], v3 offset:1024
	ds_read_b128 v[142:145], v3 offset:2048
	ds_read_b128 v[146:149], v3 offset:3072
	v_add_u32_e32 v3, s88, v221
	s_add_u32 s48, s48, 0x10000
	ds_read_b128 v[150:153], v3
	ds_read_b128 v[154:157], v3 offset:1024
	ds_read_b128 v[158:161], v3 offset:2048
	ds_read_b128 v[162:165], v3 offset:3072
	s_addc_u32 s49, s49, 0
	s_add_u32 s50, s27, s46
	s_addc_u32 s51, s45, s47
	s_cmp_eq_u32 s46, 0x70000
	s_cselect_b32 s70, s1, s48
	s_cselect_b32 s71, s0, s49
	s_cselect_b32 s50, s21, s50
	s_cselect_b32 s51, s19, s51
	s_add_u32 s48, s70, 0x8000
	s_addc_u32 s49, s71, 0
	v_lshl_add_u64 v[4:5], v[182:183], 0, s[46:47]
	s_add_i32 m0, s74, 0xc000
	ds_read_b128 v[166:169], v225
	ds_read_b128 v[170:173], v225 offset:1024
	ds_read_b128 v[174:177], v225 offset:2048
	ds_read_b128 v[178:181], v225 offset:3072
	ds_read_b128 v[186:189], v225 offset:4096
	ds_read_b128 v[190:193], v225 offset:5120
	ds_read_b128 v[194:197], v225 offset:6144
	ds_read_b128 v[228:231], v225 offset:7168
	global_load_lds_dwordx4 v[4:5], off
	v_lshl_add_u64 v[4:5], v[184:185], 0, s[46:47]
	s_add_i32 m0, s74, 0xe000
	s_nop 0
	global_load_lds_dwordx4 v[4:5], off
	s_waitcnt vmcnt(8)
	s_waitcnt lgkmcnt(0)
	s_setprio 1
	s_barrier
	v_mfma_f32_16x16x32_bf16 v[130:133], v[134:137], v[166:169], 0
	v_mfma_f32_16x16x32_bf16 v[126:129], v[142:145], v[166:169], 0
	v_mfma_f32_16x16x32_bf16 v[114:117], v[134:137], v[174:177], 0
	v_mfma_f32_16x16x32_bf16 v[110:113], v[142:145], v[174:177], 0
	v_mfma_f32_16x16x32_bf16 v[98:101], v[134:137], v[186:189], 0
	v_mfma_f32_16x16x32_bf16 v[94:97], v[142:145], v[186:189], 0
	v_mfma_f32_16x16x32_bf16 v[82:85], v[134:137], v[194:197], 0
	v_mfma_f32_16x16x32_bf16 v[78:81], v[142:145], v[194:197], 0
	v_mfma_f32_16x16x32_bf16 v[130:133], v[138:141], v[170:173], v[130:133]
	v_mfma_f32_16x16x32_bf16 v[126:129], v[146:149], v[170:173], v[126:129]
	v_mfma_f32_16x16x32_bf16 v[114:117], v[138:141], v[178:181], v[114:117]
	v_mfma_f32_16x16x32_bf16 v[110:113], v[146:149], v[178:181], v[110:113]
	v_mfma_f32_16x16x32_bf16 v[98:101], v[138:141], v[190:193], v[98:101]
	v_mfma_f32_16x16x32_bf16 v[94:97], v[146:149], v[190:193], v[94:97]
	v_mfma_f32_16x16x32_bf16 v[82:85], v[138:141], v[228:231], v[82:85]
	v_mfma_f32_16x16x32_bf16 v[78:81], v[146:149], v[228:231], v[78:81]
	s_setprio 0
	s_setprio 1
	v_mfma_f32_16x16x32_bf16 v[122:125], v[150:153], v[166:169], 0
	v_mfma_f32_16x16x32_bf16 v[118:121], v[158:161], v[166:169], 0
	v_mfma_f32_16x16x32_bf16 v[106:109], v[150:153], v[174:177], 0
	v_mfma_f32_16x16x32_bf16 v[102:105], v[158:161], v[174:177], 0
	v_mfma_f32_16x16x32_bf16 v[90:93], v[150:153], v[186:189], 0
	v_mfma_f32_16x16x32_bf16 v[86:89], v[158:161], v[186:189], 0
	v_mfma_f32_16x16x32_bf16 v[74:77], v[150:153], v[194:197], 0
	v_mfma_f32_16x16x32_bf16 v[70:73], v[158:161], v[194:197], 0
	v_mfma_f32_16x16x32_bf16 v[122:125], v[154:157], v[170:173], v[122:125]
	v_mfma_f32_16x16x32_bf16 v[118:121], v[162:165], v[170:173], v[118:121]
	v_mfma_f32_16x16x32_bf16 v[106:109], v[154:157], v[178:181], v[106:109]
	v_mfma_f32_16x16x32_bf16 v[102:105], v[162:165], v[178:181], v[102:105]
	v_mfma_f32_16x16x32_bf16 v[90:93], v[154:157], v[190:193], v[90:93]
	v_mfma_f32_16x16x32_bf16 v[86:89], v[162:165], v[190:193], v[86:89]
	v_mfma_f32_16x16x32_bf16 v[74:77], v[154:157], v[228:231], v[74:77]
	v_mfma_f32_16x16x32_bf16 v[70:73], v[162:165], v[228:231], v[70:73]
	s_barrier
	s_setprio 0
	s_add_i32 s52, s87, s73
	s_mov_b32 m0, s52
	ds_read_b128 v[166:169], v225 offset:16384
	ds_read_b128 v[170:173], v225 offset:17408
	ds_read_b128 v[174:177], v225 offset:18432
	ds_read_b128 v[178:181], v225 offset:19456
	ds_read_b128 v[186:189], v225 offset:20480
	ds_read_b128 v[190:193], v225 offset:21504
	ds_read_b128 v[194:197], v225 offset:22528
	ds_read_b128 v[228:231], v225 offset:23552
	global_load_lds_dwordx4 v200, s[50:51]
	s_add_i32 m0, s52, 0x2000
	s_add_u32 s52, s50, 0x1000
	s_addc_u32 s53, s51, 0
	s_add_i32 s54, s88, s73
	global_load_lds_dwordx4 v204, s[50:51]
	s_mov_b32 m0, s54
	s_nop 0
	global_load_lds_dwordx4 v200, s[52:53]
	s_add_i32 m0, s54, 0x2000
	s_nop 0
	global_load_lds_dwordx4 v204, s[52:53]
	s_mov_b32 m0, s74
	s_nop 0
	global_load_lds_dwordx4 v198, s[70:71]
	s_mov_b32 m0, s75
	s_nop 0
	global_load_lds_dwordx4 v202, s[70:71]
	s_waitcnt vmcnt(8)
	s_waitcnt lgkmcnt(0)
	s_setprio 1
	s_barrier
; #define PG8_STAGE(bufoff, gbase, voff) do { _Pragma("unroll") for (int _i = 0; _i < 2; ++_i) \
;         __builtin_amdgcn_global_load_lds((const unsigned*)((const char*)(gbase) + (voff)[_i]), (PG8_LAS unsigned*)(lds + (bufoff) + ldsw + _i * 8192), 16, 0, 0); } while (0)
; #define PG8_LDA(dst, b, h) do { _Pragma("unroll") for (int m = 0; m < 4; ++m) _Pragma("unroll") for (int k = 0; k < 2; ++k) dst[m][k] = *(const PG8_LAS bf16x8*)(lds + PG8_SA(b, h) + aoff + m * 2048 + k * 1024); } while (0)
; #define PG8_LDB(dst, b, h) do { _Pragma("unroll") for (int n = 0; n < 2; ++n) _Pragma("unroll") for (int k = 0; k < 2; ++k) dst[n][k] = *(const PG8_LAS bf16x8*)(lds + PG8_SB(b, h) + boff + n * 2048 + k * 1024); } while (0)
; #define PG8_MMA(ai, bj, At, Bt) do { __builtin_amdgcn_s_setprio(1); _Pragma("unroll") for (int m = 0; m < 4; ++m) _Pragma("unroll") for (int n = 0; n < 2; ++n) _Pragma("unroll") for (int k = 0; k < 2; ++k) \
;         acc[ai][bj][m][n] = __builtin_amdgcn_mfma_f32_16x16x32_bf16(Bt[n][k], At[m][k], acc[ai][bj][m][n], 0, 0, 0); __builtin_amdgcn_s_setprio(0); } while (0)
; #define PG8_WAIT_V(n) asm volatile("s_waitcnt vmcnt(" #n ")" ::: "memory")
; #define PG8_WAIT_L(n) asm volatile("s_waitcnt lgkmcnt(" #n ")" ::: "memory")
; #define PG8_BAR __builtin_amdgcn_s_barrier()
; #define PG8_SCHED __builtin_amdgcn_sched_barrier(0)
; template <class Epi, class Sched, bool ALIGN_EPI = false, bool SP2 = false>
; __device__ __forceinline__ void gemm_phase(PG8_LAS unsigned char* lds, const Gemm g, const Sched& S, const Epi& E) {
;     ...
;             PG8_WAIT_V(8); PG8_WAIT_L(0); PG8_BAR; PG8_MMA(1, 0, At, B0); PG8_MMA(1, 1, At, B1); PG8_BAR; PG8_SCHED;
;             PG8_LDB(B0, 1, 0); PG8_LDB(B1, 1, 1); PG8_SCHED; PG8_LDA(At, 1, 0); PG8_STAGE(PG8_SA(0, 1), a2 + hstep, voffA);
;             PG8_WAIT_V(8); PG8_WAIT_L(0); PG8_BAR; PG8_MMA(0, 0, At, B0); PG8_MMA(0, 1, At, B1); PG8_BAR; PG8_SCHED;
	v_mfma_f32_16x16x32_bf16 v[66:69], v[134:137], v[166:169], 0
	v_mfma_f32_16x16x32_bf16 v[62:65], v[142:145], v[166:169], 0
	v_mfma_f32_16x16x32_bf16 v[50:53], v[134:137], v[174:177], 0
	v_mfma_f32_16x16x32_bf16 v[46:49], v[142:145], v[174:177], 0
	v_mfma_f32_16x16x32_bf16 v[34:37], v[134:137], v[186:189], 0
	v_mfma_f32_16x16x32_bf16 v[30:33], v[142:145], v[186:189], 0
	v_mfma_f32_16x16x32_bf16 v[18:21], v[134:137], v[194:197], 0
	v_mfma_f32_16x16x32_bf16 v[14:17], v[142:145], v[194:197], 0
	v_mfma_f32_16x16x32_bf16 v[66:69], v[138:141], v[170:173], v[66:69]
	v_mfma_f32_16x16x32_bf16 v[62:65], v[146:149], v[170:173], v[62:65]
	v_mfma_f32_16x16x32_bf16 v[50:53], v[138:141], v[178:181], v[50:53]
	v_mfma_f32_16x16x32_bf16 v[46:49], v[146:149], v[178:181], v[46:49]
	v_mfma_f32_16x16x32_bf16 v[34:37], v[138:141], v[190:193], v[34:37]
	v_mfma_f32_16x16x32_bf16 v[30:33], v[146:149], v[190:193], v[30:33]
	v_mfma_f32_16x16x32_bf16 v[18:21], v[138:141], v[228:231], v[18:21]
	v_mfma_f32_16x16x32_bf16 v[14:17], v[146:149], v[228:231], v[14:17]
	s_setprio 0
	s_setprio 1
	v_mfma_f32_16x16x32_bf16 v[58:61], v[150:153], v[166:169], 0
	v_mfma_f32_16x16x32_bf16 v[54:57], v[158:161], v[166:169], 0
	v_mfma_f32_16x16x32_bf16 v[42:45], v[150:153], v[174:177], 0
	v_mfma_f32_16x16x32_bf16 v[38:41], v[158:161], v[174:177], 0
	v_mfma_f32_16x16x32_bf16 v[26:29], v[150:153], v[186:189], 0
	v_mfma_f32_16x16x32_bf16 v[22:25], v[158:161], v[186:189], 0
	v_mfma_f32_16x16x32_bf16 v[10:13], v[150:153], v[194:197], 0
	v_mfma_f32_16x16x32_bf16 v[4:7], v[158:161], v[194:197], 0
	v_mfma_f32_16x16x32_bf16 v[58:61], v[154:157], v[170:173], v[58:61]
	v_mfma_f32_16x16x32_bf16 v[54:57], v[162:165], v[170:173], v[54:57]
	v_mfma_f32_16x16x32_bf16 v[42:45], v[154:157], v[178:181], v[42:45]
	v_mfma_f32_16x16x32_bf16 v[38:41], v[162:165], v[178:181], v[38:41]
	v_mfma_f32_16x16x32_bf16 v[26:29], v[154:157], v[190:193], v[26:29]
	v_mfma_f32_16x16x32_bf16 v[22:25], v[162:165], v[190:193], v[22:25]
	v_mfma_f32_16x16x32_bf16 v[10:13], v[154:157], v[228:231], v[10:13]
	v_mfma_f32_16x16x32_bf16 v[4:7], v[162:165], v[228:231], v[4:7]
	s_barrier
	s_setprio 0
	s_add_i32 s54, 0, 0x18000
	v_add_u32_e32 v3, s54, v221
	s_add_i32 s55, 0, 0x1c000
	ds_read_b128 v[134:137], v3
	ds_read_b128 v[138:141], v3 offset:1024
	ds_read_b128 v[142:145], v3 offset:2048
	ds_read_b128 v[146:149], v3 offset:3072
	v_add_u32_e32 v3, s55, v221
	ds_read_b128 v[150:153], v3
	ds_read_b128 v[154:157], v3 offset:1024
	ds_read_b128 v[158:161], v3 offset:2048
	ds_read_b128 v[162:165], v3 offset:3072
	s_add_u32 s52, s70, 0x4000
	s_addc_u32 s53, s71, 0
	s_mov_b32 m0, s77
	ds_read_b128 v[166:169], v225 offset:32768
	ds_read_b128 v[170:173], v225 offset:33792
	ds_read_b128 v[174:177], v225 offset:34816
	ds_read_b128 v[178:181], v225 offset:35840
	ds_read_b128 v[186:189], v225 offset:36864
	ds_read_b128 v[190:193], v225 offset:37888
	ds_read_b128 v[194:197], v225 offset:38912
	ds_read_b128 v[228:231], v225 offset:39936
	global_load_lds_dwordx4 v198, s[52:53]
	s_mov_b32 m0, s78
	s_nop 0
	global_load_lds_dwordx4 v202, s[52:53]
	s_waitcnt vmcnt(8)
	s_waitcnt lgkmcnt(0)
	s_setprio 1
	s_barrier
	v_mfma_f32_16x16x32_bf16 v[130:133], v[134:137], v[166:169], v[130:133]
	v_mfma_f32_16x16x32_bf16 v[126:129], v[142:145], v[166:169], v[126:129]
	v_mfma_f32_16x16x32_bf16 v[114:117], v[134:137], v[174:177], v[114:117]
	v_mfma_f32_16x16x32_bf16 v[110:113], v[142:145], v[174:177], v[110:113]
	v_mfma_f32_16x16x32_bf16 v[98:101], v[134:137], v[186:189], v[98:101]
	v_mfma_f32_16x16x32_bf16 v[94:97], v[142:145], v[186:189], v[94:97]
	v_mfma_f32_16x16x32_bf16 v[82:85], v[134:137], v[194:197], v[82:85]
	v_mfma_f32_16x16x32_bf16 v[78:81], v[142:145], v[194:197], v[78:81]
	v_mfma_f32_16x16x32_bf16 v[130:133], v[138:141], v[170:173], v[130:133]
	v_mfma_f32_16x16x32_bf16 v[126:129], v[146:149], v[170:173], v[126:129]
	v_mfma_f32_16x16x32_bf16 v[114:117], v[138:141], v[178:181], v[114:117]
	v_mfma_f32_16x16x32_bf16 v[110:113], v[146:149], v[178:181], v[110:113]
	v_mfma_f32_16x16x32_bf16 v[98:101], v[138:141], v[190:193], v[98:101]
	v_mfma_f32_16x16x32_bf16 v[94:97], v[146:149], v[190:193], v[94:97]
	v_mfma_f32_16x16x32_bf16 v[82:85], v[138:141], v[228:231], v[82:85]
	v_mfma_f32_16x16x32_bf16 v[78:81], v[146:149], v[228:231], v[78:81]
	s_setprio 0
	s_setprio 1
	v_mfma_f32_16x16x32_bf16 v[122:125], v[150:153], v[166:169], v[122:125]
	v_mfma_f32_16x16x32_bf16 v[118:121], v[158:161], v[166:169], v[118:121]
	v_mfma_f32_16x16x32_bf16 v[106:109], v[150:153], v[174:177], v[106:109]
	v_mfma_f32_16x16x32_bf16 v[102:105], v[158:161], v[174:177], v[102:105]
	v_mfma_f32_16x16x32_bf16 v[90:93], v[150:153], v[186:189], v[90:93]
	v_mfma_f32_16x16x32_bf16 v[86:89], v[158:161], v[186:189], v[86:89]
	v_mfma_f32_16x16x32_bf16 v[74:77], v[150:153], v[194:197], v[74:77]
	v_mfma_f32_16x16x32_bf16 v[70:73], v[158:161], v[194:197], v[70:73]
	v_mfma_f32_16x16x32_bf16 v[122:125], v[154:157], v[170:173], v[122:125]
	v_mfma_f32_16x16x32_bf16 v[118:121], v[162:165], v[170:173], v[118:121]
	v_mfma_f32_16x16x32_bf16 v[106:109], v[154:157], v[178:181], v[106:109]
	v_mfma_f32_16x16x32_bf16 v[102:105], v[162:165], v[178:181], v[102:105]
	v_mfma_f32_16x16x32_bf16 v[90:93], v[154:157], v[190:193], v[90:93]
	v_mfma_f32_16x16x32_bf16 v[86:89], v[162:165], v[190:193], v[86:89]
	v_mfma_f32_16x16x32_bf16 v[74:77], v[154:157], v[228:231], v[74:77]
	v_mfma_f32_16x16x32_bf16 v[70:73], v[162:165], v[228:231], v[70:73]
	s_barrier
; #define PG8_STAGE(bufoff, gbase, voff) do { _Pragma("unroll") for (int _i = 0; _i < 2; ++_i) \
;         __builtin_amdgcn_global_load_lds((const unsigned*)((const char*)(gbase) + (voff)[_i]), (PG8_LAS unsigned*)(lds + (bufoff) + ldsw + _i * 8192), 16, 0, 0); } while (0)
; #define PG8_LDA(dst, b, h) do { _Pragma("unroll") for (int m = 0; m < 4; ++m) _Pragma("unroll") for (int k = 0; k < 2; ++k) dst[m][k] = *(const PG8_LAS bf16x8*)(lds + PG8_SA(b, h) + aoff + m * 2048 + k * 1024); } while (0)
; #define PG8_MMA(ai, bj, At, Bt) do { __builtin_amdgcn_s_setprio(1); _Pragma("unroll") for (int m = 0; m < 4; ++m) _Pragma("unroll") for (int n = 0; n < 2; ++n) _Pragma("unroll") for (int k = 0; k < 2; ++k) \
;         acc[ai][bj][m][n] = __builtin_amdgcn_mfma_f32_16x16x32_bf16(Bt[n][k], At[m][k], acc[ai][bj][m][n], 0, 0, 0); __builtin_amdgcn_s_setprio(0); } while (0)
; #define PG8_WAIT_V(n) asm volatile("s_waitcnt vmcnt(" #n ")" ::: "memory")
; #define PG8_WAIT_L(n) asm volatile("s_waitcnt lgkmcnt(" #n ")" ::: "memory")
; #define PG8_BAR __builtin_amdgcn_s_barrier()
; #define PG8_SCHED __builtin_amdgcn_sched_barrier(0)
; template <class Epi, class Sched, bool ALIGN_EPI = false, bool SP2 = false>
; __device__ __forceinline__ void gemm_phase(PG8_LAS unsigned char* lds, const Gemm g, const Sched& S, const Epi& E) {
;     ...
;             PG8_LDA(At, 1, 1); PG8_STAGE(PG8_SB(1, 0), b3, voffB); PG8_STAGE(PG8_SB(1, 1), b3 + hstepB, voffB); PG8_STAGE(PG8_SA(1, 0), a3, voffA);
;             PG8_WAIT_V(8); PG8_WAIT_L(0); PG8_BAR; PG8_MMA(1, 0, At, B0); PG8_MMA(1, 1, At, B1); PG8_BAR; PG8_SCHED;
	s_setprio 0
	s_add_u32 s52, s50, 0x8000
	s_addc_u32 s53, s51, 0
	s_add_i32 s54, s54, s73
	s_mov_b32 m0, s54
	ds_read_b128 v[166:169], v225 offset:49152
	ds_read_b128 v[170:173], v225 offset:50176
	ds_read_b128 v[174:177], v225 offset:51200
	ds_read_b128 v[178:181], v225 offset:52224
	ds_read_b128 v[186:189], v225 offset:53248
	ds_read_b128 v[190:193], v225 offset:54272
	ds_read_b128 v[194:197], v225 offset:55296
	ds_read_b128 v[228:231], v225 offset:56320
	global_load_lds_dwordx4 v200, s[52:53]
	s_add_i32 m0, s54, 0x2000
	s_add_u32 s50, s50, 0x9000
	v_lshl_add_u64 v[8:9], s[52:53], 0, v[204:205]
	s_addc_u32 s51, s51, 0
	s_add_i32 s52, s55, s73
	global_load_lds_dwordx4 v[8:9], off
	s_mov_b32 m0, s52
	s_nop 0
	global_load_lds_dwordx4 v200, s[50:51]
	s_add_i32 m0, s52, 0x2000
	s_nop 0
	global_load_lds_dwordx4 v204, s[50:51]
	s_mov_b32 m0, s81
	s_nop 0
	global_load_lds_dwordx4 v198, s[48:49]
	s_mov_b32 m0, s82
	s_nop 0
	global_load_lds_dwordx4 v202, s[48:49]
	s_waitcnt vmcnt(8)
	s_waitcnt lgkmcnt(0)
	s_setprio 1
	s_barrier
	v_mfma_f32_16x16x32_bf16 v[66:69], v[134:137], v[166:169], v[66:69]
	v_mfma_f32_16x16x32_bf16 v[62:65], v[142:145], v[166:169], v[62:65]
	v_mfma_f32_16x16x32_bf16 v[50:53], v[134:137], v[174:177], v[50:53]
	v_mfma_f32_16x16x32_bf16 v[46:49], v[142:145], v[174:177], v[46:49]
	v_mfma_f32_16x16x32_bf16 v[34:37], v[134:137], v[186:189], v[34:37]
	v_mfma_f32_16x16x32_bf16 v[30:33], v[142:145], v[186:189], v[30:33]
	v_mfma_f32_16x16x32_bf16 v[18:21], v[134:137], v[194:197], v[18:21]
	v_mfma_f32_16x16x32_bf16 v[14:17], v[142:145], v[194:197], v[14:17]
	v_mfma_f32_16x16x32_bf16 v[66:69], v[138:141], v[170:173], v[66:69]
	v_mfma_f32_16x16x32_bf16 v[62:65], v[146:149], v[170:173], v[62:65]
	v_mfma_f32_16x16x32_bf16 v[50:53], v[138:141], v[178:181], v[50:53]
	v_mfma_f32_16x16x32_bf16 v[46:49], v[146:149], v[178:181], v[46:49]
	v_mfma_f32_16x16x32_bf16 v[34:37], v[138:141], v[190:193], v[34:37]
	v_mfma_f32_16x16x32_bf16 v[30:33], v[146:149], v[190:193], v[30:33]
	v_mfma_f32_16x16x32_bf16 v[18:21], v[138:141], v[228:231], v[18:21]
	v_mfma_f32_16x16x32_bf16 v[14:17], v[146:149], v[228:231], v[14:17]
	s_setprio 0
	s_setprio 1
	v_mfma_f32_16x16x32_bf16 v[58:61], v[150:153], v[166:169], v[58:61]
	v_mfma_f32_16x16x32_bf16 v[54:57], v[158:161], v[166:169], v[54:57]
	v_mfma_f32_16x16x32_bf16 v[42:45], v[150:153], v[174:177], v[42:45]
	v_mfma_f32_16x16x32_bf16 v[38:41], v[158:161], v[174:177], v[38:41]
	v_mfma_f32_16x16x32_bf16 v[26:29], v[150:153], v[186:189], v[26:29]
	v_mfma_f32_16x16x32_bf16 v[22:25], v[158:161], v[186:189], v[22:25]
	v_mfma_f32_16x16x32_bf16 v[8:11], v[150:153], v[194:197], v[10:13]
	v_mfma_f32_16x16x32_bf16 v[4:7], v[158:161], v[194:197], v[4:7]
	v_mfma_f32_16x16x32_bf16 v[58:61], v[154:157], v[170:173], v[58:61]
	v_mfma_f32_16x16x32_bf16 v[54:57], v[162:165], v[170:173], v[54:57]
	v_mfma_f32_16x16x32_bf16 v[42:45], v[154:157], v[178:181], v[42:45]
	v_mfma_f32_16x16x32_bf16 v[38:41], v[162:165], v[178:181], v[38:41]
	v_mfma_f32_16x16x32_bf16 v[26:29], v[154:157], v[190:193], v[26:29]
	v_mfma_f32_16x16x32_bf16 v[22:25], v[162:165], v[190:193], v[22:25]
	v_mfma_f32_16x16x32_bf16 v[10:13], v[154:157], v[228:231], v[8:11]
	v_mfma_f32_16x16x32_bf16 v[6:9], v[162:165], v[228:231], v[4:7]
	s_barrier
	s_setprio 0
	s_add_i32 s56, s56, 2
	s_add_u32 s46, s46, 0x10000
	s_addc_u32 s47, s47, 0
	s_branch .LBB0_381
